# grid barriers at in-layer seams become XCC-local when a runtime census shows every blockIdx%8 group sits on one XCC (else unchanged full barrier); k_pe prep loop remapped to the same token ownership
# speedup vs baseline: 1.0378x; 1.0137x over previous
; #define LAS __attribute__((address_space(3)))
; __device__ __forceinline__ unsigned xb_add(unsigned* p, unsigned v) { return __hip_atomic_fetch_add(p, v, __ATOMIC_RELAXED, __HIP_MEMORY_SCOPE_AGENT); }
; __device__ __forceinline__ unsigned xb_xcc_id() { return (unsigned)__builtin_amdgcn_s_getreg((3 << 11) | 20) & 0xFu; }
; __device__ __forceinline__ XcdBarrier xcd_barrier_post(unsigned* bar, volatile LAS unsigned* st) {
;     XcdBarrier b; b.bar = bar; b.x = xb_xcc_id(); b.st = st;
;     if (threadIdx.x == 0) (void)xb_add(&bar[XB_XCNT(b.x)], 1u);
;     return b;
; }
; __global__ void __launch_bounds__(512) fwd_megakernel(KArgs a) {
;     ...
;     const int wave = __builtin_amdgcn_readfirstlane(threadIdx.x >> 6);
;     const int G = gridDim.x, bx = blockIdx.x;
;     volatile LAS unsigned* MISC = (volatile LAS unsigned*)(lds + 131072);
;     if (threadIdx.x < 16) MISC[threadIdx.x] = 0u;
;     __syncthreads();
;     XcdBarrier xbar = xcd_barrier_post((unsigned*)(a.ws + WS_CTL), MISC + 8);
_Z14fwd_megakernel5KArgs:
	s_load_dwordx2 s[68:69], s[0:1], 0xb0
	s_load_dwordx4 s[4:7], s[0:1], 0xa0
	s_load_dword s71, s[0:1], 0xc8
	s_load_dwordx2 s[84:85], s[0:1], 0xc0
	v_and_b32_e32 v202, 0x3ff, v0
	v_cmp_gt_u32_e32 vcc, 16, v202
	s_waitcnt lgkmcnt(0)
	v_writelane_b32 v252, s4, 0
	s_nop 1
	v_writelane_b32 v252, s5, 1
	v_writelane_b32 v252, s6, 2
	v_writelane_b32 v252, s7, 3
	s_load_dwordx8 s[4:11], s[0:1], 0x80
	s_waitcnt lgkmcnt(0)
	v_writelane_b32 v252, s4, 4
	s_nop 1
	v_writelane_b32 v252, s5, 5
	v_writelane_b32 v252, s6, 6
	v_writelane_b32 v252, s7, 7
	v_writelane_b32 v252, s8, 8
	v_writelane_b32 v252, s9, 9
	v_writelane_b32 v252, s10, 10
	v_writelane_b32 v252, s11, 11
	s_add_u32 s8, s0, 0xc0
	s_addc_u32 s9, s1, 0
	v_readfirstlane_b32 s10, v202
	s_and_saveexec_b64 s[4:5], vcc
	v_lshl_add_u32 v1, v202, 2, 0
	v_add_u32_e32 v1, 0x20000, v1
	v_mov_b32_e32 v2, 0
	ds_write_b32 v1, v2
	s_or_b64 exec, exec, s[4:5]
	s_waitcnt lgkmcnt(0)
	s_barrier
	s_add_u32 s26, s68, 0xb00000
	s_getreg_b32 s3, hwreg(HW_REG_XCC_ID, 0, 4)
	s_addc_u32 s27, s69, 0
	s_and_b32 s73, s3, 15
	v_cmp_eq_u32_e64 s[96:97], 0, v202
	s_and_saveexec_b64 s[4:5], s[96:97]
	s_cbranch_execz .LBB0_5
	s_mov_b64 s[6:7], exec
	v_mbcnt_lo_u32_b32 v1, s6, 0
	v_mbcnt_hi_u32_b32 v1, s7, v1
	v_cmp_eq_u32_e32 vcc, 0, v1
	s_and_b64 s[12:13], exec, vcc
	s_mov_b64 exec, s[12:13]
	s_cbranch_execz .LBB0_5
	s_lshl_b32 s3, s73, 8
	s_bcnt1_i32_b64 s6, s[6:7]
	v_mov_b32_e32 v1, s3
	v_mov_b32_e32 v2, s6
	global_atomic_add v1, v2, s[26:27] offset:1024
	s_and_b32 s3, s2, 7
	s_lshl_b32 s3, s3, 4
	s_add_i32 s3, s3, s73
	s_lshl_b32 s3, s3, 2
	s_add_i32 s3, s3, 0x4000
	v_mov_b32_e32 v1, s3
	v_mov_b32_e32 v3, 0x2002c
	global_atomic_add v1, v2, s[26:27]
	ds_write_b32 v3, v1

; #define GRID_SYNC() do { xcd_barrier(xbar); } while (0)
; __global__ void __launch_bounds__(512) fwd_megakernel(KArgs a) {
;     ...
;     const int vcu = (G % 8 == 0) ? (bx % 8) * (G / 8) + bx / 8 : bx;
;     const int gw = vcu * NWAVES + wave, NGW = G * NWAVES;
;     unsigned char* ws = a.ws;
;     float* ssq = (float*)(ws + WS_SSQ);
;     float* cosT = (float*)(ws + WS_COS); float* sinT = (float*)(ws + WS_SIN);
;     float* lutG = (float*)(ws + WS_LUT); float* kmeanG = (float*)(ws + WS_KMEAN);
;     bf16* XB = (bf16*)(ws + WS_XB);
;     ...
;     if (a.use_cg_sync) { grid.sync(); __builtin_amdgcn_fence(__ATOMIC_ACQUIRE, "agent"); } else GRID_SYNC();
; #pragma unroll 1
;     for (int layer = 0; layer < 4; ++layer) {
;         const int j = layer >> 1; const bool is_mla = (layer & 1) == 0;
;         float* ssq_attn = ssq + (size_t)SSQ_ATTN * TOK * 16; float* ssq_attn_next = ssq_attn; float* ssq_mlp = ssq + (size_t)SSQ_MLP * TOK * 16;
;         const bf16* Oattn; const bf16* Wo_t;
;         unsigned char* wbl = is_mla ? (ws + WS_WMLA + j * W_MLA_SZ) : (ws + WS_WMOBA + j * W_MOBA_SZ);
;         bf16* CQ = (bf16*)(ws + WS_CQ); bf16* CKV = (bf16*)(ws + WS_CKV); bf16* KPE = (bf16*)(ws + WS_KPE);
;         bf16* Q = (bf16*)(ws + WS_Q); bf16* KN = (bf16*)(ws + WS_KN); bf16* VRAW = (bf16*)(ws + WS_VRAW);
;         bf16* QKV = (bf16*)(ws + WS_QKV);
;         float* ssq_cq = ssq + (size_t)SSQ_CQ * TOK * 16; float* ssq_ckv = ssq + (size_t)SSQ_CKV * TOK * 16;
.LBB0_162:
	s_and_saveexec_b64 s[0:1], s[96:97]
	s_cbranch_execz .Lxm2_done
	v_mov_b32_e32 v0, 0x2002c
	ds_read_b32 v0, v0
	s_waitcnt lgkmcnt(0)
	v_add_u32_e32 v0, 0xb00000, v0
	global_load_dword v1, v0, s[68:69] sc1
	s_lshr_b32 s3, s84, 3
	s_waitcnt vmcnt(0)
	v_readfirstlane_b32 s4, v1
	s_nop 3
	s_cmp_eq_u32 s4, s3
	s_cbranch_scc1 .Lxm2_done
	v_mov_b32_e32 v0, 0xb04400
	v_mov_b32_e32 v1, 1
	global_atomic_add v0, v1, s[68:69]
.Lxm2_done:
	s_or_b64 exec, exec, s[0:1]
	s_add_u32 s0, s68, 0x1f400000
	s_addc_u32 s1, s69, 0
	s_add_u32 s76, s68, 0x200000
	s_addc_u32 s77, s69, 0
	s_add_u32 s78, s68, 0x600000
	s_addc_u32 s79, s69, 0
	s_add_u32 s62, s68, 0xa00000
	s_addc_u32 s63, s69, 0
	s_add_u32 s66, s68, 0xa80000
	s_addc_u32 s67, s69, 0
	s_mov_b64 s[4:5], s[68:69]
	s_add_u32 s68, s4, 0x6800000
	v_writelane_b32 v252, s0, 30
	s_addc_u32 s69, s5, 0
	v_mov_b32_e32 v181, 0
	v_writelane_b32 v252, s1, 31
	s_add_u32 s0, s4, 0x1f600000
	s_addc_u32 s1, s5, 0
	v_writelane_b32 v252, s0, 32
	v_mov_b32_e32 v204, 0x358637bd
	v_mov_b32_e32 v205, 0x260
	v_writelane_b32 v252, s1, 33
	s_add_u32 s0, s4, 0x1cc00000
	s_addc_u32 s1, s5, 0
	v_writelane_b32 v252, s0, 34
	v_mov_b32_e32 v182, 0x43000000
	v_mbcnt_hi_u32_b32 v206, -1, v76
	v_writelane_b32 v252, s1, 35
	s_add_u32 s0, s4, 0x1e400000
	s_addc_u32 s1, s5, 0
	s_add_u32 s86, s4, 0x1c800000
	s_addc_u32 s87, s5, 0
	s_add_u32 s88, s4, 0xa800000
	s_addc_u32 s89, s5, 0
	s_add_u32 s90, s4, 0x10800000
	s_addc_u32 s91, s5, 0
	s_add_u32 s92, s4, 0x14800000
	v_writelane_b32 v252, s0, 36
	s_addc_u32 s93, s5, 0
	v_mov_b32_e32 v207, 0xff800000
	v_writelane_b32 v252, s1, 37
	s_add_u32 s0, s4, 0x1fa00000
	s_addc_u32 s1, s5, 0
	v_writelane_b32 v252, s0, 38
	v_mov_b32_e32 v208, 0x139fc
	v_mov_b32_e32 v209, 0xf149f2ca
	v_writelane_b32 v252, s1, 39
	s_add_u32 s0, s4, 0x1f800000
	s_addc_u32 s1, s5, 0
	v_writelane_b32 v252, s0, 40
	s_cmpk_lt_i32 s2, 0x180
	s_movk_i32 s36, 0x300
	v_writelane_b32 v252, s1, 41
	s_cselect_b64 s[0:1], -1, 0
	v_writelane_b32 v252, s0, 42
	s_ashr_i32 s3, s2, 31
	s_ashr_i32 s33, s84, 31
	v_writelane_b32 v252, s1, 43
	s_lshr_b32 s0, s3, 29
	s_add_i32 s0, s2, s0
	s_ashr_i32 s13, s0, 3
	s_and_b32 s0, s0, -8
	s_sub_i32 s14, s2, s0
	s_add_u32 s80, s4, 0xb00200
	s_addc_u32 s81, s5, 0
	s_add_u32 s16, s4, 0xb00400
	s_addc_u32 s17, s5, 0
	s_add_u32 s18, s4, 0xb00500
	s_addc_u32 s19, s5, 0
	s_add_u32 s64, s4, 0xb00600
	s_addc_u32 s65, s5, 0
	s_add_u32 s0, s4, 0xb00700
	s_addc_u32 s1, s5, 0
	v_writelane_b32 v252, s0, 44
	s_mov_b32 s51, 0
	s_mov_b64 s[58:59], 0x80
	v_writelane_b32 v252, s1, 45
	s_add_u32 s0, s4, 0xb00800
	s_addc_u32 s1, s5, 0
	v_writelane_b32 v252, s0, 46
	s_mov_b32 s94, 0x3dd53b94
	s_nop 0
	v_writelane_b32 v252, s1, 47
	s_add_u32 s0, s4, 0xb00900
	s_addc_u32 s1, s5, 0
	v_writelane_b32 v252, s0, 48
	s_nop 1
	v_writelane_b32 v252, s1, 49
	s_add_u32 s0, s4, 0xb00a00
	s_addc_u32 s1, s5, 0
	v_writelane_b32 v252, s0, 50
	s_nop 1
	v_writelane_b32 v252, s1, 51
	s_add_u32 s0, s4, 0xb00b00
	s_addc_u32 s1, s5, 0
	v_writelane_b32 v252, s0, 52
	s_nop 1
	v_writelane_b32 v252, s1, 53
	s_add_u32 s0, s4, 0xb00c00
	s_addc_u32 s1, s5, 0
	v_writelane_b32 v252, s0, 54
	s_nop 1
	v_writelane_b32 v252, s1, 55
	s_add_u32 s0, s4, 0xb00d00
	s_addc_u32 s1, s5, 0
	v_writelane_b32 v252, s0, 56
	s_nop 1
	v_writelane_b32 v252, s1, 57
	s_add_u32 s0, s4, 0xb00e00
	s_addc_u32 s1, s5, 0
	v_writelane_b32 v252, s0, 58
	s_nop 1
	v_writelane_b32 v252, s1, 59
	s_add_u32 s0, s4, 0xb00f00
	s_addc_u32 s1, s5, 0
	v_writelane_b32 v252, s0, 60
	s_nop 1
	v_writelane_b32 v252, s1, 61
	s_add_u32 s0, s4, 0xb01000
	s_addc_u32 s1, s5, 0
	v_writelane_b32 v252, s0, 62
	s_nop 1
	v_writelane_b32 v252, s1, 63
	s_add_u32 s0, s4, 0xb01100
	s_addc_u32 s1, s5, 0
	v_writelane_b32 v253, s0, 0
	s_nop 1
	v_writelane_b32 v253, s1, 1
	s_add_u32 s0, s4, 0xb01200
	s_addc_u32 s1, s5, 0
	v_writelane_b32 v253, s0, 2
	s_nop 1
	v_writelane_b32 v253, s1, 3
	s_add_u32 s0, s4, 0xb01300
	s_addc_u32 s1, s5, 0
	v_writelane_b32 v253, s0, 4
	s_cmp_eq_u32 s73, 15
	s_nop 0
	v_writelane_b32 v253, s1, 5
	s_cselect_b64 s[0:1], -1, 0
	v_writelane_b32 v253, s0, 6
	s_cmp_eq_u32 s73, 14
	s_nop 0
	v_writelane_b32 v253, s1, 7
	s_cselect_b64 s[0:1], -1, 0
	v_writelane_b32 v253, s0, 8
	s_cmp_eq_u32 s73, 13
	s_nop 0
	v_writelane_b32 v253, s1, 9
	s_cselect_b64 s[0:1], -1, 0
	v_writelane_b32 v253, s0, 10
	s_cmp_eq_u32 s73, 12
	s_nop 0
	v_writelane_b32 v253, s1, 11
	s_cselect_b64 s[0:1], -1, 0
	v_writelane_b32 v253, s0, 12
	s_cmp_eq_u32 s73, 11
	s_nop 0
	v_writelane_b32 v253, s1, 13
	s_cselect_b64 s[0:1], -1, 0
	v_writelane_b32 v253, s0, 14
	s_cmp_eq_u32 s73, 10
	s_nop 0
	v_writelane_b32 v253, s1, 15
	s_cselect_b64 s[0:1], -1, 0
	v_writelane_b32 v253, s0, 16
	s_cmp_eq_u32 s73, 9
	s_nop 0
	v_writelane_b32 v253, s1, 17
	s_cselect_b64 s[0:1], -1, 0
	v_writelane_b32 v253, s0, 18
	s_cmp_eq_u32 s73, 8
	s_nop 0
	v_writelane_b32 v253, s1, 19
	s_cselect_b64 s[0:1], -1, 0
	v_writelane_b32 v253, s0, 20
	s_cmp_eq_u32 s73, 7
	s_nop 0
	v_writelane_b32 v253, s1, 21
	s_cselect_b64 s[0:1], -1, 0
	v_writelane_b32 v253, s0, 22
	s_cmp_eq_u32 s73, 6
	s_nop 0
	v_writelane_b32 v253, s1, 23
	s_cselect_b64 s[0:1], -1, 0
	v_writelane_b32 v253, s0, 24
	s_cmp_eq_u32 s73, 5
	s_nop 0
	v_writelane_b32 v253, s1, 25
	s_cselect_b64 s[0:1], -1, 0
	v_writelane_b32 v253, s0, 26
	s_cmp_eq_u32 s73, 4
	s_nop 0
	v_writelane_b32 v253, s1, 27
	s_cselect_b64 s[0:1], -1, 0
	v_writelane_b32 v253, s0, 28
	s_cmp_eq_u32 s73, 3
	s_nop 0
	v_writelane_b32 v253, s1, 29
	s_cselect_b64 s[0:1], -1, 0
	v_writelane_b32 v253, s0, 30
	s_cmp_eq_u32 s73, 2
	s_nop 0
	v_writelane_b32 v253, s1, 31
	s_cselect_b64 s[0:1], -1, 0
	v_writelane_b32 v253, s0, 32
;     __host__ __device__ bool next(int i, Unit& u) const {
;         const long L = (long)i * G + c; if (L >= nwg) return false;
;         int wgid = (int)L; { const int q = nwg / NXCD, r = nwg % NXCD, xcd = wgid % NXCD, off = wgid / NXCD; wgid = (xcd < r ? xcd * (q + 1) : r * (q + 1) + (xcd - r) * q) + off; }
;         const int nig = WGM * nN, gid = wgid / nig, fm = gid * WGM, gsz = (nM - fm) < WGM ? (nM - fm) : WGM;
;         u.pm = fm + ((wgid % nig) % gsz); u.pn = (wgid % nig) / gsz; return true;
;     }
;     __host__ __device__ bool next(int i, Unit& u) const { const int nr = nwg / G; if (i >= nr) return false; return StaticOrder::next(nr - 1 - i, u); }
	s_cmp_eq_u32 s73, 1
	s_nop 0
	v_writelane_b32 v253, s1, 33
	s_cselect_b64 s[0:1], -1, 0
	v_writelane_b32 v253, s0, 34
	s_cmp_eq_u32 s73, 0
	s_nop 0
	v_writelane_b32 v253, s1, 35
	s_cselect_b64 s[0:1], -1, 0
	v_writelane_b32 v253, s0, 36
	s_nop 1
	v_writelane_b32 v253, s1, 37
	s_lshl_b32 s0, s73, 8
	s_add_u32 s0, s26, s0
	s_addc_u32 s1, s27, 0
	s_add_u32 s6, s0, 0x1400
	s_addc_u32 s7, s1, 0
	v_writelane_b32 v253, s6, 38
	s_add_u32 s0, s0, 0x2400
	s_addc_u32 s1, s1, 0
	v_writelane_b32 v253, s7, 39
	v_writelane_b32 v253, s0, 40
	s_nop 1
	v_writelane_b32 v253, s1, 41
	s_add_u32 s0, s4, 0xb03400
	s_addc_u32 s1, s5, 0
	v_writelane_b32 v253, s0, 42
	s_nop 1
	v_writelane_b32 v253, s1, 43
	s_add_u32 s0, s4, 0xb03500
	s_addc_u32 s1, s5, 0
	v_writelane_b32 v253, s0, 44
	s_nop 1
	v_writelane_b32 v253, s1, 45
	s_lshl_b32 s0, s70, 3
	s_cmpk_lt_i32 s70, 0x1000
	v_writelane_b32 v253, s0, 46
	s_cselect_b64 s[0:1], -1, 0
	v_writelane_b32 v253, s0, 47
	s_nop 1
	v_writelane_b32 v253, s1, 48
	s_lshl_b32 s0, s84, 6
	s_cmpk_lt_i32 s2, 0x300
	v_writelane_b32 v253, s0, 49
	s_cselect_b64 s[0:1], -1, 0
	s_add_u32 s95, s4, 0xa800800
	s_addc_u32 s8, s5, 0
	s_add_u32 s9, s4, 0xa801000
	v_writelane_b32 v253, s0, 50
	s_addc_u32 s10, s5, 0
	s_nop 0
	v_writelane_b32 v253, s1, 51
	s_add_u32 s0, s4, 0x1a800000
	s_addc_u32 s1, s5, 0
	v_writelane_b32 v253, s0, 52
	s_cmpk_lt_i32 s74, 0x100
	s_nop 0
	v_writelane_b32 v253, s1, 53
	s_cselect_b64 s[0:1], -1, 0
	v_writelane_b32 v253, s0, 54
	s_nop 1
	v_writelane_b32 v253, s1, 55
	s_add_u32 s0, s4, 0x18800000
	v_writelane_b32 v253, s4, 56
	s_addc_u32 s1, s5, 0
	s_cmpk_lt_i32 s2, 0x200
	v_writelane_b32 v253, s5, 57
	v_writelane_b32 v253, s0, 58
	s_movk_i32 s4, 0x61
	s_nop 0
	v_writelane_b32 v253, s1, 59
	s_cselect_b64 s[0:1], -1, 0
	v_writelane_b32 v253, s0, 60
	s_nop 1
	v_writelane_b32 v253, s1, 61
	s_lshl_b32 s0, s14, 6
	s_cmp_lt_i32 s14, 0
	s_mul_i32 s1, s14, 0x41
	s_cselect_b32 s0, s1, s0
	s_cselect_b32 s1, 49, 48
	s_mul_i32 s1, s14, s1
	s_cselect_b32 s4, s4, 0x60
	s_add_i32 s1, s1, s13
	s_mul_hi_i32 s5, s1, 0x2aaaaaab
	s_lshr_b32 s6, s5, 31
	s_ashr_i32 s5, s5, 2
	s_add_i32 s5, s5, s6
	s_mul_i32 s6, s5, 24
	s_sub_i32 s1, s1, s6
	s_bfe_i32 s6, s1, 0x80000
	s_bfe_u32 s6, s6, 0x3000c
	s_add_i32 s6, s1, s6
	s_mul_i32 s4, s14, s4
	s_and_b32 s7, s6, 0xf8
	s_add_i32 s4, s4, s13
	s_sub_i32 s1, s1, s7
	s_mul_hi_i32 s7, s4, 0x2aaaaaab
	s_lshr_b32 s11, s7, 31
	s_ashr_i32 s7, s7, 3
	s_add_i32 s7, s7, s11
	s_mul_i32 s11, s7, 48
	s_sub_i32 s4, s4, s11
	s_bfe_i32 s11, s4, 0x80000
	s_bfe_u32 s11, s11, 0x3000c
	s_add_i32 s11, s4, s11
	s_and_b32 s12, s11, 0xf8
	s_sub_i32 s4, s4, s12
	s_lshl_b32 s7, s7, 3
	s_sext_i32_i8 s4, s4
	s_add_i32 s0, s0, s13
	s_add_i32 s15, s7, s4
	s_ashr_i32 s4, s0, 31
	s_lshr_b32 s4, s4, 27
	s_add_i32 s4, s0, s4
	s_and_b32 s7, s4, 0xffe0
	s_sub_i32 s0, s0, s7
	s_bfe_i32 s7, s0, 0x80000
	s_bfe_u32 s7, s7, 0x3000c
	s_add_i32 s7, s0, s7
	s_and_b32 s12, s7, 0xf8
	s_sub_i32 s12, s0, s12
	s_lshl_b32 s0, s5, 3
	s_sext_i32_i8 s1, s1
	s_bfe_i32 s5, s6, 0x80000
	s_add_i32 s6, s0, s1
	s_bfe_i32 s0, s11, 0x80000
	s_sext_i32_i16 s0, s0
	v_writelane_b32 v253, s13, 62
	s_ashr_i32 s1, s0, 3
	s_lshr_b32 s0, s0, 3
	v_writelane_b32 v253, s1, 63
	s_bfe_i64 s[0:1], s[0:1], 0x100000
	v_writelane_b32 v254, s0, 0
	s_sext_i32_i16 s5, s5
	s_movk_i32 s11, 0xc00
	v_writelane_b32 v254, s1, 1
	s_ashr_i32 s0, s4, 5
	s_bfe_i32 s1, s7, 0x80000
	s_lshl_b32 s0, s0, 3
	s_sext_i32_i16 s4, s1
	s_sext_i32_i8 s1, s12
	s_add_i32 s12, s0, s1
	s_ashr_i32 s0, s5, 3
	v_writelane_b32 v254, s0, 2
	s_lshr_b32 s0, s5, 3
	s_bfe_i64 s[0:1], s[0:1], 0x100000
	s_lshl_b64 s[0:1], s[0:1], 19
	v_writelane_b32 v254, s0, 3
	s_ashr_i32 s7, s6, 31
	s_nop 0
	v_writelane_b32 v254, s1, 4
	v_writelane_b32 v254, s15, 5
	s_ashr_i32 s0, s15, 31
	v_writelane_b32 v254, s0, 6
	s_ashr_i32 s0, s4, 3
	v_writelane_b32 v254, s0, 7
	s_lshr_b32 s0, s4, 3
	s_mov_b32 s4, s6
	v_writelane_b32 v254, s4, 8
	s_nop 1
	v_writelane_b32 v254, s5, 9
	s_lshl_b64 s[4:5], s[6:7], 19
	s_add_u32 s4, s68, s4
	s_addc_u32 s5, s69, s5
	s_add_u32 s6, s4, 0x40000
	v_writelane_b32 v254, s4, 10
	s_addc_u32 s7, s5, 0
	s_abs_i32 s1, s84
	v_cvt_f32_u32_e32 v0, s1
	v_writelane_b32 v254, s5, 11
	v_writelane_b32 v254, s6, 12
	s_sub_i32 s4, 0, s1
	v_rcp_iflag_f32_e32 v0, v0
	v_writelane_b32 v254, s7, 13
	s_ashr_i32 s13, s12, 31
	v_writelane_b32 v254, s12, 14
	v_mul_f32_e32 v0, 0x4f7ffffe, v0
	v_cvt_u32_f32_e32 v0, v0
	v_writelane_b32 v254, s13, 15
	s_bfe_i64 s[6:7], s[0:1], 0x100000
	v_writelane_b32 v254, s6, 16
	v_readfirstlane_b32 s5, v0
	s_mul_i32 s4, s4, s5
	s_mul_hi_u32 s4, s5, s4
	s_add_i32 s5, s5, s4
	s_lshr_b32 s0, s5, 21
	v_writelane_b32 v254, s7, 17
	s_mul_i32 s4, s0, s1
	s_sub_i32 s4, 0x800, s4
	v_writelane_b32 v254, s14, 18
	s_lshr_b32 s5, s14, 31
	v_writelane_b32 v254, s5, 19
	s_add_i32 s5, s0, 1
	s_sub_i32 s6, s4, s1
	s_cmp_ge_u32 s4, s1
	s_cselect_b32 s0, s5, s0
	s_cselect_b32 s4, s6, s4
	s_add_i32 s5, s0, 1
	s_cmp_ge_u32 s4, s1
	s_cselect_b32 s0, s5, s0
	s_xor_b32 s0, s0, s33
	s_sub_i32 s37, s0, s33
	s_mul_i32 s1, s85, s84
	s_cmp_gt_i32 s37, 0
	s_mul_i32 s85, s1, s71
	s_cselect_b64 s[0:1], -1, 0
	v_writelane_b32 v254, s0, 20
	v_mov_b64_e32 v[0:1], 0x800
	s_movk_i32 s12, 0x140
	v_writelane_b32 v254, s1, 21
	s_add_i32 s0, s37, -1
	s_mul_i32 s1, s0, s33
	s_mul_hi_u32 s4, s0, s84
	s_add_i32 s4, s4, s1
	s_mul_i32 s0, s0, s84
	s_add_u32 s0, s0, s2
	s_addc_u32 s1, s4, s3
	s_ashr_i32 s4, s0, 31
	s_lshr_b32 s4, s4, 29
	s_add_i32 s4, s0, s4
	s_ashr_i32 s5, s4, 3
	s_and_b32 s4, s4, -8
	s_sub_i32 s4, s0, s4
	s_cmp_gt_i32 s4, -1
	v_writelane_b32 v254, s5, 22
	s_cselect_b64 s[6:7], -1, 0
	v_writelane_b32 v254, s6, 23
	s_lshl_b32 s5, s72, 3
	v_cmp_lt_i64_e64 s[0:1], s[0:1], v[0:1]
	v_writelane_b32 v254, s7, 24
	s_lshl_b32 s6, s74, 6
	v_writelane_b32 v254, s74, 25
	s_add_i32 s5, s6, s5
	v_writelane_b32 v254, s5, 26
	v_writelane_b32 v254, s0, 27
	s_mov_b64 s[74:75], s[16:17]
	s_mov_b64 s[72:73], s[18:19]
	v_writelane_b32 v254, s1, 28
	s_lshl_b32 s0, s4, 8
	v_writelane_b32 v254, s0, 29
	s_mul_i32 s0, s4, 0x101
	v_writelane_b32 v254, s0, 30
	s_add_i32 s0, s37, -2
	v_writelane_b32 v254, s0, 31
	s_lshl_b32 s0, s84, 11
	v_writelane_b32 v254, s0, 32
	s_add_i32 s0, 0, 0x20020
	v_writelane_b32 v254, s0, 33
	s_add_i32 s0, 0, 0x20024
	v_writelane_b32 v254, s0, 34
	s_add_i32 s0, 0, 0x22100
	v_writelane_b32 v254, s0, 35
	s_add_i32 s0, 0, 0x22900
	v_writelane_b32 v254, s0, 36
	v_writelane_b32 v254, s96, 37
	s_mov_b32 s14, 0xffff
	s_mov_b32 s5, 0
	v_writelane_b32 v254, s97, 38
	v_writelane_b32 v254, s76, 39
	s_nop 1
	v_writelane_b32 v254, s77, 40
	v_writelane_b32 v254, s78, 41
	s_nop 1
	v_writelane_b32 v254, s79, 42
	v_writelane_b32 v254, s80, 43
	s_nop 1
	v_writelane_b32 v254, s81, 44
	v_writelane_b32 v254, s74, 45
	s_nop 1
	v_writelane_b32 v254, s75, 46
	v_writelane_b32 v254, s72, 47
	s_nop 1
	v_writelane_b32 v254, s73, 48
	v_writelane_b32 v254, s62, 49
	s_nop 1
	v_writelane_b32 v254, s63, 50
	v_writelane_b32 v254, s64, 51
	s_nop 1
	v_writelane_b32 v254, s65, 52
	s_branch .LBB0_166

; __device__ __forceinline__ unsigned xb_add(unsigned* p, unsigned v) { return __hip_atomic_fetch_add(p, v, __ATOMIC_RELAXED, __HIP_MEMORY_SCOPE_AGENT); }
; __device__ __forceinline__ void xcd_barrier(const XcdBarrier& b) {
;     ...
;         const unsigned old = xb_add(&bar[XB_XSUB(b.x)], 1u);
;         const unsigned gen = old / nloc;
;         if (old + 1u == (gen + 1u) * nloc) {
;             __builtin_amdgcn_fence(__ATOMIC_RELEASE, "agent");
;             asm volatile("s_waitcnt vmcnt(0)" ::: "memory");
;             const unsigned og = xb_add(&bar[XB_TOP], 1u);
;             const unsigned tg = og / nx;
;             if (og + 1u == (tg + 1u) * nx) xb_add(&bar[XB_TOPGEN], 1u);
.LBB0_444:
	s_andn2_saveexec_b64 s[4:5], s[4:5]
	s_cbranch_execz .LBB0_464
	s_mov_b64 s[4:5], exec
	v_mov_b32_e32 v1, 0x20028
	ds_read_b32 v1, v1
	s_waitcnt lgkmcnt(0)
	v_cmp_ne_u32_e32 vcc, 0, v1
	s_cbranch_vccnz .Lxb_local_0
	buffer_wbl2 sc1
	s_waitcnt lgkmcnt(0)
	s_waitcnt vmcnt(0)
	v_mbcnt_lo_u32_b32 v1, s4, 0
	v_mbcnt_hi_u32_b32 v1, s5, v1
	v_cmp_eq_u32_e32 vcc, 0, v1
	s_and_saveexec_b64 s[6:7], vcc
	s_cbranch_execz .LBB0_447
	s_bcnt1_i32_b64 s4, s[4:5]
	v_mov_b32_e32 v2, s4
	v_readlane_b32 s4, v253, 42
	v_readlane_b32 s5, v253, 43
	s_nop 4
	global_atomic_add v2, v181, v2, s[4:5] sc0

; __device__ __forceinline__ unsigned xb_add(unsigned* p, unsigned v) { return __hip_atomic_fetch_add(p, v, __ATOMIC_RELAXED, __HIP_MEMORY_SCOPE_AGENT); }
; __device__ __forceinline__ void xcd_barrier(const XcdBarrier& b) {
;     ...
;             __builtin_amdgcn_fence(__ATOMIC_ACQUIRE, "agent");
;             xb_add(&bar[XB_XGEN(b.x)], 1u);
;             asm volatile("s_waitcnt vmcnt(0)" ::: "memory");
.Lxb_local_0:
	s_mov_b64 s[4:5], exec
	v_mbcnt_lo_u32_b32 v0, s4, 0
	v_mbcnt_hi_u32_b32 v0, s5, v0
	v_cmp_eq_u32_e32 vcc, 0, v0
	s_waitcnt vmcnt(0)
	buffer_inv sc1
	s_and_saveexec_b64 s[6:7], vcc
	s_cbranch_execz .LBB0_463
	s_bcnt1_i32_b64 s4, s[4:5]
	v_mov_b32_e32 v0, s4
	v_readlane_b32 s4, v253, 40
	v_readlane_b32 s5, v253, 41
	s_nop 4
	global_atomic_add v181, v0, s[4:5]

; #define OPAQUE_TID() int tid = threadIdx.x; asm volatile("" : "+v"(tid)); const int lane = tid & 63
; __global__ void __launch_bounds__(512) fwd_megakernel(KArgs a) {
;     ...
;                 OPAQUE_TID();
;                 const float* g_kr = a.mla_kr + j * 64;
;                 float gr[8];
; #pragma unroll
;                 for (int e = 0; e < 8; ++e) gr[e] = g_kr[8 * (lane & 7) + e];
;                 for (int t0 = gw * 8; t0 < TOK; t0 += NGW * 8) {
;                     const int tok = t0 + (lane >> 3), c = lane & 7;
;                     bf16* ptr = KPE + (size_t)tok * 64 + c * 8;
;                     const u32x4 v = *(const u32x4*)ptr;
;                     const f32x4 c0 = *(const f32x4*)(cosT + tok * 32 + 8 * (c & 3)), c1 = *(const f32x4*)(cosT + tok * 32 + 8 * (c & 3) + 4);
;                     const f32x4 s0 = *(const f32x4*)(sinT + tok * 32 + 8 * (c & 3)), s1 = *(const f32x4*)(sinT + tok * 32 + 8 * (c & 3) + 4);
;                     float f[8]; unpack8(v, f);
;                     float ss = 0.f;
; #pragma unroll
;                     for (int e = 0; e < 8; ++e) ss += f[e] * f[e];
;                     ss += __shfl_xor(ss, 1); ss += __shfl_xor(ss, 2); ss += __shfl_xor(ss, 4);
;                     const float sc = __builtin_amdgcn_rsqf(ss * (1.0f / 64.0f) + pg8::RMS_EPS_F);
;                     float y[8];
; #pragma unroll
;                     for (int e = 0; e < 8; ++e) y[e] = f[e] * sc * gr[e];
; #pragma unroll
;                     for (int e = 0; e < 8; ++e) { const float pe = __shfl_xor(y[e], 4); const float cc = e < 4 ? c0[e & 3] : c1[e & 3], sn = e < 4 ? s0[e & 3] : s1[e & 3];
;                         y[e] = (c & 4) ? (y[e] * cc + pe * sn) : (y[e] * cc - pe * sn); }
;                     *(u32x4*)ptr = pack8(y);
;                 }
;             }
.LBB0_464:
	s_or_b64 exec, exec, s[0:1]
	s_and_saveexec_b64 s[0:1], s[96:97]
	s_cbranch_execz .Lxm3_done
	v_readlane_b32 s4, v253, 42
	v_readlane_b32 s5, v253, 43
	v_mov_b32_e32 v0, 0x1000
	s_nop 4
	global_load_dword v1, v0, s[4:5] sc1
	s_waitcnt vmcnt(0)
	v_readfirstlane_b32 s4, v1
	s_nop 3
	s_cmp_lg_u32 s4, 0
	s_cbranch_scc1 .Lxm3_done
	v_mov_b32_e32 v0, 0x20028
	v_mov_b32_e32 v1, 1
	ds_write_b32 v0, v1
	s_waitcnt lgkmcnt(0)
.Lxm3_done:
	s_or_b64 exec, exec, s[0:1]
	v_readlane_b32 s0, v253, 47
	v_readlane_b32 s1, v253, 48
	v_readlane_b32 s70, v254, 54
	v_mov_b32_e32 v14, v202
	s_andn2_b64 vcc, exec, s[0:1]
	v_readlane_b32 s4, v253, 49
	v_readlane_b32 s5, v254, 32
	v_readlane_b32 s71, v254, 55
	s_waitcnt lgkmcnt(0)
	s_barrier
	s_cbranch_vccnz .LBB0_467
	v_readlane_b32 s16, v252, 12
	v_readlane_b32 s0, v254, 62
	v_readlane_b32 s17, v252, 13
	v_readlane_b32 s18, v252, 14
	v_readlane_b32 s19, v252, 15
	v_readlane_b32 s20, v252, 16
	v_readlane_b32 s21, v252, 17
	v_readlane_b32 s22, v252, 18
	v_readlane_b32 s23, v252, 19
	s_lshl_b32 s50, s0, 6
	v_readlane_b32 s24, v252, 20
	v_readlane_b32 s25, v252, 21
	v_readlane_b32 s26, v252, 22
	v_readlane_b32 s27, v252, 23
	s_mov_b64 s[16:17], s[20:21]
	s_lshl_b64 s[0:1], s[50:51], 2
	s_mov_b64 s[18:19], s[22:23]
	s_mov_b64 s[20:21], s[24:25]
	s_mov_b64 s[22:23], s[26:27]
	v_lshlrev_b32_e32 v0, 3, v14
	s_add_u32 s0, s22, s0
	v_and_b32_e32 v8, 56, v0
	s_addc_u32 s1, s23, s1
	v_lshlrev_b32_e32 v4, 2, v8
	global_load_dwordx4 v[0:3], v4, s[0:1] offset:16
	s_nop 0
	global_load_dwordx4 v[4:7], v4, s[0:1]
	v_and_b32_e32 v17, 64, v206
	v_xor_b32_e32 v15, 1, v206
	v_add_u32_e32 v19, 64, v17
	v_cmp_lt_i32_e32 vcc, v15, v19
	v_lshlrev_b32_e32 v180, 1, v8
	v_lshlrev_b32_e32 v10, 5, v14
	v_cndmask_b32_e32 v15, v206, v15, vcc
	v_lshlrev_b32_e32 v17, 2, v15
	v_xor_b32_e32 v15, 2, v206
	v_cmp_lt_i32_e32 vcc, v15, v19
	v_bfe_u32 v16, v14, 3, 3
	v_lshl_add_u64 v[8:9], s[86:87], 0, v[180:181]
	v_cndmask_b32_e32 v15, v206, v15, vcc
	v_lshlrev_b32_e32 v18, 2, v15
	v_xor_b32_e32 v15, 4, v206
	v_cmp_lt_i32_e32 vcc, v15, v19
	v_and_b32_e32 v180, 0x60, v10
	v_and_b32_e32 v14, 4, v14
	v_cndmask_b32_e32 v15, v206, v15, vcc
	v_readlane_b32 s0, v254, 26
	v_lshl_add_u64 v[10:11], s[76:77], 0, v[180:181]
	v_lshl_add_u64 v[12:13], s[78:79], 0, v[180:181]
	v_lshlrev_b32_e32 v19, 2, v15
	v_cmp_eq_u32_e32 vcc, 0, v14
	v_add_lshl_u32 v14, s0, v16, 5
	v_readlane_b32 s0, v253, 46
	v_readlane_b32 s28, v252, 24
	v_readlane_b32 s29, v252, 25
	v_readlane_b32 s30, v252, 26
	v_readlane_b32 s31, v252, 27
	s_nop 1
	s_lshr_b32 s1, s0, 11
	s_lshl_b32 s1, s1, 11
	s_add_i32 s0, s0, s1
	s_lshl_b32 s1, s1, 5
	v_add_u32_e32 v14, s1, v14
.LBB0_466:
	s_nop 0
	v_add_u32_e32 v20, s0, v16
	v_ashrrev_i32_e32 v21, 31, v20
	v_lshlrev_b64 v[20:21], 7, v[20:21]
	v_lshl_add_u64 v[40:41], v[8:9], 0, v[20:21]
	global_load_dwordx4 v[20:23], v[40:41], off
	v_ashrrev_i32_e32 v15, 31, v14
	v_lshlrev_b64 v[32:33], 2, v[14:15]
	v_lshl_add_u64 v[28:29], v[10:11], 0, v[32:33]
	v_lshl_add_u64 v[36:37], v[12:13], 0, v[32:33]
	global_load_dwordx4 v[24:27], v[28:29], off offset:16
	s_nop 0
	global_load_dwordx4 v[28:31], v[28:29], off
	s_nop 0
	global_load_dwordx4 v[32:35], v[36:37], off offset:16
	s_nop 0
	global_load_dwordx4 v[36:39], v[36:37], off
	s_addk_i32 s0, 0x800
	v_add_u32_e32 v14, 0x10000, v14
	s_bitcmp0_b32 s0, 11
	s_waitcnt vmcnt(4)
	v_lshlrev_b32_e32 v52, 16, v20
	v_and_b32_e32 v53, 0xffff0000, v20
	v_lshlrev_b32_e32 v48, 16, v21
	v_and_b32_e32 v49, 0xffff0000, v21
	v_pk_mul_f32 v[20:21], v[52:53], v[52:53]
	v_pk_mul_f32 v[50:51], v[48:49], v[48:49]
	v_add_f32_e32 v15, v20, v21
	v_lshlrev_b32_e32 v46, 16, v22
	v_and_b32_e32 v47, 0xffff0000, v22
	v_add_f32_e32 v15, v15, v50
	v_lshlrev_b32_e32 v42, 16, v23
	v_and_b32_e32 v43, 0xffff0000, v23
	v_pk_mul_f32 v[22:23], v[46:47], v[46:47]
	v_add_f32_e32 v15, v15, v51
	v_add_f32_e32 v15, v15, v22
	v_pk_mul_f32 v[44:45], v[42:43], v[42:43]
	v_add_f32_e32 v15, v15, v23
	v_add_f32_e32 v15, v15, v44
	v_add_f32_e32 v15, v15, v45
	ds_bpermute_b32 v20, v17, v15
	s_waitcnt lgkmcnt(0)
	v_add_f32_e32 v15, v15, v20
	ds_bpermute_b32 v20, v18, v15
	s_waitcnt lgkmcnt(0)
	v_add_f32_e32 v15, v15, v20
	ds_bpermute_b32 v20, v19, v15
	s_waitcnt lgkmcnt(0)
	v_add_f32_e32 v15, v15, v20
	v_fmamk_f32 v15, v15, 0x3c800000, v204
	v_rsq_f32_e32 v20, v15
	s_nop 0
	v_pk_mul_f32 v[22:23], v[20:21], v[52:53] op_sel_hi:[0,1]
	v_pk_mul_f32 v[22:23], v[22:23], v[4:5]
	v_pk_mul_f32 v[44:45], v[20:21], v[48:49] op_sel_hi:[0,1]
	v_pk_mul_f32 v[46:47], v[20:21], v[46:47] op_sel_hi:[0,1]
	v_pk_mul_f32 v[20:21], v[20:21], v[42:43] op_sel_hi:[0,1]
	ds_bpermute_b32 v42, v19, v22
	ds_bpermute_b32 v43, v19, v23
	v_pk_mul_f32 v[44:45], v[44:45], v[6:7]
	v_pk_mul_f32 v[46:47], v[46:47], v[0:1]
	v_pk_mul_f32 v[20:21], v[20:21], v[2:3]
	s_waitcnt vmcnt(0) lgkmcnt(0)
	v_pk_mul_f32 v[36:37], v[36:37], v[42:43]
	s_nop 0
	v_cndmask_b32_e64 v37, v37, -v37, vcc
	v_cndmask_b32_e64 v36, v36, -v36, vcc
	v_pk_fma_f32 v[22:23], v[22:23], v[28:29], v[36:37]
	ds_bpermute_b32 v28, v19, v44
	ds_bpermute_b32 v29, v19, v45
	s_waitcnt lgkmcnt(0)
	v_pk_mul_f32 v[28:29], v[38:39], v[28:29]
	s_nop 0
	v_cndmask_b32_e64 v29, v29, -v29, vcc
	v_cndmask_b32_e64 v28, v28, -v28, vcc
	v_pk_fma_f32 v[28:29], v[44:45], v[30:31], v[28:29]
	ds_bpermute_b32 v30, v19, v46
	ds_bpermute_b32 v31, v19, v47
	s_waitcnt lgkmcnt(0)
	v_pk_mul_f32 v[30:31], v[32:33], v[30:31]
	s_nop 0
	v_cndmask_b32_e64 v31, v31, -v31, vcc
	v_cndmask_b32_e64 v30, v30, -v30, vcc
	v_pk_fma_f32 v[24:25], v[46:47], v[24:25], v[30:31]
	ds_bpermute_b32 v30, v19, v20
	ds_bpermute_b32 v31, v19, v21
	s_waitcnt lgkmcnt(0)
	v_pk_mul_f32 v[30:31], v[34:35], v[30:31]
	s_nop 0
	v_cndmask_b32_e64 v31, v31, -v31, vcc
	v_cndmask_b32_e64 v30, v30, -v30, vcc
	v_pk_fma_f32 v[26:27], v[20:21], v[26:27], v[30:31]
	v_cvt_pk_bf16_f32 v20, v22, v23
	v_cvt_pk_bf16_f32 v21, v28, v29
	v_cvt_pk_bf16_f32 v22, v24, v25
	v_cvt_pk_bf16_f32 v23, v26, v27
	global_store_dwordx4 v[40:41], v[20:23], off
	s_cbranch_scc0 .LBB0_466

; __device__ __forceinline__ unsigned xb_add(unsigned* p, unsigned v) { return __hip_atomic_fetch_add(p, v, __ATOMIC_RELAXED, __HIP_MEMORY_SCOPE_AGENT); }
; __device__ __forceinline__ void xcd_barrier(const XcdBarrier& b) {
;     ...
;         const unsigned old = xb_add(&bar[XB_XSUB(b.x)], 1u);
;         const unsigned gen = old / nloc;
;         if (old + 1u == (gen + 1u) * nloc) {
;             __builtin_amdgcn_fence(__ATOMIC_RELEASE, "agent");
;             asm volatile("s_waitcnt vmcnt(0)" ::: "memory");
;             const unsigned og = xb_add(&bar[XB_TOP], 1u);
;             const unsigned tg = og / nx;
;             if (og + 1u == (tg + 1u) * nx) xb_add(&bar[XB_TOPGEN], 1u);
.LBB0_853:
	s_andn2_saveexec_b64 s[6:7], s[6:7]
	s_cbranch_execz .LBB0_873
	s_mov_b64 s[6:7], exec
	v_mov_b32_e32 v1, 0x20028
	ds_read_b32 v1, v1
	s_waitcnt lgkmcnt(0)
	v_cmp_ne_u32_e32 vcc, 0, v1
	s_cbranch_vccnz .Lxb_local_2
	buffer_wbl2 sc1
	s_waitcnt lgkmcnt(0)
	s_waitcnt vmcnt(0)
	v_mbcnt_lo_u32_b32 v1, s6, 0
	v_mbcnt_hi_u32_b32 v1, s7, v1
	v_cmp_eq_u32_e32 vcc, 0, v1
	s_and_saveexec_b64 s[28:29], vcc
	s_cbranch_execz .LBB0_856
	s_bcnt1_i32_b64 s6, s[6:7]
	v_mov_b32_e32 v2, s6
	v_readlane_b32 s6, v253, 42
	v_readlane_b32 s7, v253, 43
	s_nop 4
	global_atomic_add v2, v181, v2, s[6:7] sc0

; __device__ __forceinline__ unsigned xb_add(unsigned* p, unsigned v) { return __hip_atomic_fetch_add(p, v, __ATOMIC_RELAXED, __HIP_MEMORY_SCOPE_AGENT); }
; __device__ __forceinline__ void xcd_barrier(const XcdBarrier& b) {
;     ...
;             __builtin_amdgcn_fence(__ATOMIC_ACQUIRE, "agent");
;             xb_add(&bar[XB_XGEN(b.x)], 1u);
;             asm volatile("s_waitcnt vmcnt(0)" ::: "memory");
.Lxb_local_2:
	s_mov_b64 s[6:7], exec
	v_mbcnt_lo_u32_b32 v0, s6, 0
	v_mbcnt_hi_u32_b32 v0, s7, v0
	v_cmp_eq_u32_e32 vcc, 0, v0
	s_waitcnt vmcnt(0)
	buffer_inv sc1
	s_and_saveexec_b64 s[28:29], vcc
	s_cbranch_execz .LBB0_872
	s_bcnt1_i32_b64 s6, s[6:7]
	v_mov_b32_e32 v0, s6
	v_readlane_b32 s6, v253, 40
	v_readlane_b32 s7, v253, 41
	s_nop 4
	global_atomic_add v181, v0, s[6:7]

; __device__ __forceinline__ unsigned xb_add(unsigned* p, unsigned v) { return __hip_atomic_fetch_add(p, v, __ATOMIC_RELAXED, __HIP_MEMORY_SCOPE_AGENT); }
; __device__ __forceinline__ void xcd_barrier(const XcdBarrier& b) {
;     ...
;             __builtin_amdgcn_fence(__ATOMIC_ACQUIRE, "agent");
;             xb_add(&bar[XB_XGEN(b.x)], 1u);
;             asm volatile("s_waitcnt vmcnt(0)" ::: "memory");
.Lxb_local_4:
	s_mov_b64 s[4:5], exec
	v_mbcnt_lo_u32_b32 v0, s4, 0
	v_mbcnt_hi_u32_b32 v0, s5, v0
	v_cmp_eq_u32_e32 vcc, 0, v0
	s_waitcnt vmcnt(0)
	buffer_inv sc1
	s_and_saveexec_b64 s[6:7], vcc
	s_cbranch_execz .LBB0_874
	s_bcnt1_i32_b64 s4, s[4:5]
	v_mov_b32_e32 v0, s4
	v_readlane_b32 s4, v253, 40
	v_readlane_b32 s5, v253, 41
	s_nop 4
	global_atomic_add v181, v0, s[4:5]
	s_branch .LBB0_874
